# k23: k20 + P0 cache K/V conversion loop hand-written (16 loads per thread in flight instead of 4, adaLN blocks take part)
# speedup vs baseline: 1.0036x; 1.0036x over previous
; __device__ __forceinline__ unsigned pk2(float lo, float hi) { typedef __bf16 bf16x2_t_ __attribute__((ext_vector_type(2))); f32x2 v = {lo, hi}; return __builtin_bit_cast(unsigned, __builtin_convertvector(v, bf16x2_t_)); }
; __global__ void __launch_bounds__(NTHR, 2) hymba_fwd(Params P) {
;     ...
;         const int gt = (bq >= 0) ? bq * NTHR + tid : 0x7fffffff - Gq * NTHR, NGT = Gq * NTHR;
; #pragma unroll 4
;         for (int i = gt; i < NB * PAST * 64; i += NGT) { const int row = i >> 6, ch = i & 63, b = row >> 11, j = row & 2047;
;             const f32x4 k0 = *(const f32x4*)(P.cache_k + (size_t)row * 512 + ch * 8), k1 = *(const f32x4*)(P.cache_k + (size_t)row * 512 + ch * 8 + 4);
;             const f32x4 v0 = *(const f32x4*)(P.cache_v + (size_t)row * 512 + ch * 8), v1 = *(const f32x4*)(P.cache_v + (size_t)row * 512 + ch * 8 + 4);
;             *(u32x4*)(KS + (size_t)(b * SKV + j) * 512 + ch * 8) = (u32x4){pk2(k0[0], k0[1]), pk2(k0[2], k0[3]), pk2(k1[0], k1[1]), pk2(k1[2], k1[3])};
;             *(u32x4*)(VS + (size_t)(b * SKV + j) * 512 + ch * 8) = (u32x4){pk2(v0[0], v0[1]), pk2(v0[2], v0[3]), pk2(v1[0], v1[1]), pk2(v1[2], v1[3])}; }
.LBB0_65:
	s_waitcnt lgkmcnt(0)
	s_add_u32 s54, s92, 0x25000000
	s_addc_u32 s55, s93, 0
	s_add_u32 s56, s92, 0x26100000
	s_addc_u32 s57, s93, 0
	s_add_i32 s12, s2, 0xffffffb0
	s_add_i32 s3, s2, 0xb0
	s_cmp_lt_i32 s2, 48
	s_cselect_b32 s12, s3, s12
	s_cmp_gt_i32 s12, -1
	s_cselect_b64 s[0:1], -1, 0
	s_movk_i32 s3, 0xe0
	s_lshl_b32 s10, s3, 9
	s_xor_b32 s4, s10, 0x7fffffff
	v_lshl_add_u32 v1, s12, 9, v1
	v_mov_b32_e32 v2, s4
	v_cndmask_b32_e64 v2, v2, v1, s[0:1]
	s_mov_b32 s0, 0x100000
	s_movk_i32 s11, 0x840
	v_cmp_gt_i32_e32 vcc, s0, v2
	s_and_saveexec_b64 s[4:5], vcc
	s_cbranch_execz .LBB0_73
	v_mov_b32_e32 v3, v2
	s_mov_b64 s[6:7], exec
.Lmy_cv_round:
	v_add_u32_e32 v61, s10, v3
	v_add_u32_e32 v62, s10, v61
	v_add_u32_e32 v63, s10, v62
	v_cmp_gt_i32_e64 s[16:17], s0, v61
	v_cmp_gt_i32_e64 s[18:19], s0, v62
	v_cmp_gt_i32_e64 s[20:21], s0, v63
	v_lshlrev_b32_e32 v64, 5, v3
	global_load_dwordx4 v[72:75], v64, s[40:41]
	global_load_dwordx4 v[76:79], v64, s[40:41] offset:16
	global_load_dwordx4 v[80:83], v64, s[42:43]
	global_load_dwordx4 v[84:87], v64, s[42:43] offset:16
	s_mov_b64 exec, s[16:17]
	v_lshlrev_b32_e32 v65, 5, v61
	global_load_dwordx4 v[88:91], v65, s[40:41]
	global_load_dwordx4 v[92:95], v65, s[40:41] offset:16
	global_load_dwordx4 v[96:99], v65, s[42:43]
	global_load_dwordx4 v[100:103], v65, s[42:43] offset:16
	s_mov_b64 exec, s[18:19]
	v_lshlrev_b32_e32 v66, 5, v62
	global_load_dwordx4 v[104:107], v66, s[40:41]
	global_load_dwordx4 v[108:111], v66, s[40:41] offset:16
	global_load_dwordx4 v[112:115], v66, s[42:43]
	global_load_dwordx4 v[116:119], v66, s[42:43] offset:16
	s_mov_b64 exec, s[20:21]
	v_lshlrev_b32_e32 v67, 5, v63
	global_load_dwordx4 v[120:123], v67, s[40:41]
	global_load_dwordx4 v[124:127], v67, s[40:41] offset:16
	global_load_dwordx4 v[128:131], v67, s[42:43]
	global_load_dwordx4 v[132:135], v67, s[42:43] offset:16
	s_mov_b64 exec, s[6:7]
	v_ashrrev_i32_e32 v168, 17, v3
	v_bfe_u32 v169, v3, 6, 11
	v_mad_u32_u24 v169, v168, s11, v169
	v_and_b32_e32 v168, 63, v3
	v_lshlrev_b32_e32 v168, 4, v168
	v_lshl_add_u32 v68, v169, 10, v168
	v_ashrrev_i32_e32 v168, 17, v61
	v_bfe_u32 v169, v61, 6, 11
	v_mad_u32_u24 v169, v168, s11, v169
	v_and_b32_e32 v168, 63, v61
	v_lshlrev_b32_e32 v168, 4, v168
	v_lshl_add_u32 v69, v169, 10, v168
	v_ashrrev_i32_e32 v168, 17, v62
	v_bfe_u32 v169, v62, 6, 11
	v_mad_u32_u24 v169, v168, s11, v169
	v_and_b32_e32 v168, 63, v62
	v_lshlrev_b32_e32 v168, 4, v168
	v_lshl_add_u32 v70, v169, 10, v168
	v_ashrrev_i32_e32 v168, 17, v63
	v_bfe_u32 v169, v63, 6, 11
	v_mad_u32_u24 v169, v168, s11, v169
	v_and_b32_e32 v168, 63, v63
	v_lshlrev_b32_e32 v168, 4, v168
	v_lshl_add_u32 v71, v169, 10, v168
	s_waitcnt vmcnt(12)
	v_cvt_pk_bf16_f32 v136, v72, v73
	v_cvt_pk_bf16_f32 v137, v74, v75
	v_cvt_pk_bf16_f32 v138, v76, v77
	v_cvt_pk_bf16_f32 v139, v78, v79
	v_cvt_pk_bf16_f32 v140, v80, v81
	v_cvt_pk_bf16_f32 v141, v82, v83
	v_cvt_pk_bf16_f32 v142, v84, v85
	v_cvt_pk_bf16_f32 v143, v86, v87
	s_waitcnt vmcnt(8)
	v_cvt_pk_bf16_f32 v144, v88, v89
	v_cvt_pk_bf16_f32 v145, v90, v91
	v_cvt_pk_bf16_f32 v146, v92, v93
	v_cvt_pk_bf16_f32 v147, v94, v95
	v_cvt_pk_bf16_f32 v148, v96, v97
	v_cvt_pk_bf16_f32 v149, v98, v99
	v_cvt_pk_bf16_f32 v150, v100, v101
	v_cvt_pk_bf16_f32 v151, v102, v103
	s_waitcnt vmcnt(4)
	v_cvt_pk_bf16_f32 v152, v104, v105
	v_cvt_pk_bf16_f32 v153, v106, v107
	v_cvt_pk_bf16_f32 v154, v108, v109
	v_cvt_pk_bf16_f32 v155, v110, v111
	v_cvt_pk_bf16_f32 v156, v112, v113
	v_cvt_pk_bf16_f32 v157, v114, v115
	v_cvt_pk_bf16_f32 v158, v116, v117
	v_cvt_pk_bf16_f32 v159, v118, v119
	s_waitcnt vmcnt(0)
	v_cvt_pk_bf16_f32 v160, v120, v121
	v_cvt_pk_bf16_f32 v161, v122, v123
	v_cvt_pk_bf16_f32 v162, v124, v125
	v_cvt_pk_bf16_f32 v163, v126, v127
	v_cvt_pk_bf16_f32 v164, v128, v129
	v_cvt_pk_bf16_f32 v165, v130, v131
	v_cvt_pk_bf16_f32 v166, v132, v133
	v_cvt_pk_bf16_f32 v167, v134, v135
	global_store_dwordx4 v68, v[136:139], s[54:55]
	global_store_dwordx4 v68, v[140:143], s[56:57]
	s_mov_b64 exec, s[16:17]
	global_store_dwordx4 v69, v[144:147], s[54:55]
	global_store_dwordx4 v69, v[148:151], s[56:57]
	s_mov_b64 exec, s[18:19]
	global_store_dwordx4 v70, v[152:155], s[54:55]
	global_store_dwordx4 v70, v[156:159], s[56:57]
	s_mov_b64 exec, s[20:21]
	global_store_dwordx4 v71, v[160:163], s[54:55]
	global_store_dwordx4 v71, v[164:167], s[56:57]
	v_add_u32_e32 v3, s10, v63
	v_cmp_gt_i32_e32 vcc, s0, v3
	s_and_b64 s[6:7], vcc, exec
	s_mov_b64 exec, s[6:7]
	s_cbranch_execnz .Lmy_cv_round
